# fused epilogue: f32 output tile stored as whole 128-B lines (fr / fr^8 DPP piece exchange, as the bf16 epilogues do)
# speedup vs baseline: 1.0065x; 1.0026x over previous
.Lf11_w1_a:
	global_load_dwordx4 v[226:229], v131, s[8:9] sc1
	global_load_dwordx4 v[230:233], v131, s[8:9] offset:1024 sc1
	global_load_dwordx4 v[234:237], v131, s[8:9] offset:2048 sc1
	global_load_dwordx4 v[238:241], v131, s[8:9] offset:3072 sc1
	global_load_dwordx4 v[172:175], v131, s[74:75] sc1
	global_load_dwordx4 v[176:179], v131, s[74:75] offset:1024 sc1
	global_load_dwordx4 v[180:183], v131, s[74:75] offset:2048 sc1
	global_load_dwordx4 v[184:187], v131, s[74:75] offset:3072 sc1
	s_mov_b64 s[76:77], s[24:25]
	s_mov_b32 s84, 0x3a800000
	v_mov_b32_e32 v133, 0x358637bd
	s_waitcnt vmcnt(7)
	v_add_f32_e32 v226, v226, v227
	v_add_f32_e32 v228, v228, v229
	v_add_f32_e32 v156, v226, v228
	s_waitcnt vmcnt(6)
	v_add_f32_e32 v230, v230, v231
	v_add_f32_e32 v232, v232, v233
	v_add_f32_e32 v157, v230, v232
	s_waitcnt vmcnt(5)
	v_add_f32_e32 v234, v234, v235
	v_add_f32_e32 v236, v236, v237
	v_add_f32_e32 v158, v234, v236
	s_waitcnt vmcnt(4)
	v_add_f32_e32 v238, v238, v239
	v_add_f32_e32 v240, v240, v241
	v_add_f32_e32 v159, v238, v240
	s_waitcnt vmcnt(3)
	v_add_f32_e32 v172, v172, v173
	v_add_f32_e32 v174, v174, v175
	v_add_f32_e32 v160, v172, v174
	s_waitcnt vmcnt(2)
	v_add_f32_e32 v176, v176, v177
	v_add_f32_e32 v178, v178, v179
	v_add_f32_e32 v161, v176, v178
	s_waitcnt vmcnt(1)
	v_add_f32_e32 v180, v180, v181
	v_add_f32_e32 v182, v182, v183
	v_add_f32_e32 v162, v180, v182
	s_waitcnt vmcnt(0)
	v_add_f32_e32 v184, v184, v185
	v_add_f32_e32 v186, v186, v187
	v_add_f32_e32 v163, v184, v186
	ds_bpermute_b32 v136, v134, v156
	ds_bpermute_b32 v137, v134, v157
	ds_bpermute_b32 v138, v134, v158
	ds_bpermute_b32 v139, v134, v159
	ds_bpermute_b32 v188, v134, v160
	ds_bpermute_b32 v189, v134, v161
	ds_bpermute_b32 v190, v134, v162
	ds_bpermute_b32 v191, v134, v163
	s_waitcnt lgkmcnt(0)
	v_add_f32_e32 v156, v156, v136
	v_add_f32_e32 v157, v157, v137
	v_add_f32_e32 v158, v158, v138
	v_add_f32_e32 v159, v159, v139
	v_add_f32_e32 v160, v160, v188
	v_add_f32_e32 v161, v161, v189
	v_add_f32_e32 v162, v162, v190
	v_add_f32_e32 v163, v163, v191
	ds_bpermute_b32 v136, v135, v156
	ds_bpermute_b32 v137, v135, v157
	ds_bpermute_b32 v138, v135, v158
	ds_bpermute_b32 v139, v135, v159
	ds_bpermute_b32 v188, v135, v160
	ds_bpermute_b32 v189, v135, v161
	ds_bpermute_b32 v190, v135, v162
	ds_bpermute_b32 v191, v135, v163
	s_waitcnt lgkmcnt(0)
	v_add_f32_e32 v156, v156, v136
	v_add_f32_e32 v157, v157, v137
	v_add_f32_e32 v158, v158, v138
	v_add_f32_e32 v159, v159, v139
	v_add_f32_e32 v160, v160, v188
	v_add_f32_e32 v161, v161, v189
	v_add_f32_e32 v162, v162, v190
	v_add_f32_e32 v163, v163, v191
	v_fma_f32 v156, v156, s84, v133
	v_fma_f32 v157, v157, s84, v133
	v_fma_f32 v158, v158, s84, v133
	v_fma_f32 v159, v159, s84, v133
	v_fma_f32 v160, v160, s84, v133
	v_fma_f32 v161, v161, s84, v133
	v_fma_f32 v162, v162, s84, v133
	v_fma_f32 v163, v163, s84, v133
	v_rsq_f32_e32 v194, v156
	v_rsq_f32_e32 v196, v157
	v_rsq_f32_e32 v198, v158
	v_rsq_f32_e32 v200, v159
	v_rsq_f32_e32 v202, v160
	v_rsq_f32_e32 v204, v161
	v_rsq_f32_e32 v206, v162
	v_rsq_f32_e32 v208, v163
	s_nop 0
	v_and_b32_e32 v136, 8, v170
	v_cmp_eq_u32_e64 s[88:89], 0, v136
	v_add_u32_e32 v137, 0xffff8010, v129
	v_add_u32_e32 v138, 0x8000, v129
	v_add_u32_e32 v139, 16, v129
	v_cndmask_b32_e64 v188, v137, v129, s[88:89]
	v_cndmask_b32_e64 v189, v139, v138, s[88:89]
	v_pk_mul_f32 v[124:125], v[124:125], v[194:195] op_sel_hi:[1,0]
	v_pk_mul_f32 v[126:127], v[126:127], v[194:195] op_sel_hi:[1,0]
	v_pk_mul_f32 v[120:121], v[120:121], v[194:195] op_sel_hi:[1,0]
	v_pk_mul_f32 v[122:123], v[122:123], v[194:195] op_sel_hi:[1,0]
	v_pk_mul_f32 v[116:117], v[116:117], v[194:195] op_sel_hi:[1,0]
	v_pk_mul_f32 v[118:119], v[118:119], v[194:195] op_sel_hi:[1,0]
	v_pk_mul_f32 v[112:113], v[112:113], v[194:195] op_sel_hi:[1,0]
	v_pk_mul_f32 v[114:115], v[114:115], v[194:195] op_sel_hi:[1,0]
	v_pk_mul_f32 v[124:125], v[124:125], v[210:211]
	v_pk_mul_f32 v[126:127], v[126:127], v[212:213]
	v_pk_mul_f32 v[120:121], v[120:121], v[214:215]
	v_pk_mul_f32 v[122:123], v[122:123], v[216:217]
	v_pk_mul_f32 v[116:117], v[116:117], v[218:219]
	v_pk_mul_f32 v[118:119], v[118:119], v[220:221]
	v_pk_mul_f32 v[112:113], v[112:113], v[222:223]
	v_pk_mul_f32 v[114:115], v[114:115], v[224:225]
	v_cndmask_b32_e64 v136, v124, v120, s[88:89]
	v_cndmask_b32_e64 v137, v125, v121, s[88:89]
	v_cndmask_b32_e64 v138, v126, v122, s[88:89]
	v_cndmask_b32_e64 v139, v127, v123, s[88:89]
	v_mov_b32_dpp v156, v136 row_ror:8 row_mask:0xf bank_mask:0xf
	v_mov_b32_dpp v157, v137 row_ror:8 row_mask:0xf bank_mask:0xf
	v_mov_b32_dpp v158, v138 row_ror:8 row_mask:0xf bank_mask:0xf
	v_mov_b32_dpp v159, v139 row_ror:8 row_mask:0xf bank_mask:0xf
	v_cndmask_b32_e64 v120, v120, v156, s[88:89]
	v_cndmask_b32_e64 v124, v156, v124, s[88:89]
	v_cndmask_b32_e64 v121, v121, v157, s[88:89]
	v_cndmask_b32_e64 v125, v157, v125, s[88:89]
	v_cndmask_b32_e64 v122, v122, v158, s[88:89]
	v_cndmask_b32_e64 v126, v158, v126, s[88:89]
	v_cndmask_b32_e64 v123, v123, v159, s[88:89]
	v_cndmask_b32_e64 v127, v159, v127, s[88:89]
	v_cndmask_b32_e64 v136, v116, v112, s[88:89]
	v_cndmask_b32_e64 v137, v117, v113, s[88:89]
	v_cndmask_b32_e64 v138, v118, v114, s[88:89]
	v_cndmask_b32_e64 v139, v119, v115, s[88:89]
	v_mov_b32_dpp v156, v136 row_ror:8 row_mask:0xf bank_mask:0xf
	v_mov_b32_dpp v157, v137 row_ror:8 row_mask:0xf bank_mask:0xf
	v_mov_b32_dpp v158, v138 row_ror:8 row_mask:0xf bank_mask:0xf
	v_mov_b32_dpp v159, v139 row_ror:8 row_mask:0xf bank_mask:0xf
	v_cndmask_b32_e64 v112, v112, v156, s[88:89]
	v_cndmask_b32_e64 v116, v156, v116, s[88:89]
	v_cndmask_b32_e64 v113, v113, v157, s[88:89]
	v_cndmask_b32_e64 v117, v157, v117, s[88:89]
	v_cndmask_b32_e64 v114, v114, v158, s[88:89]
	v_cndmask_b32_e64 v118, v158, v118, s[88:89]
	v_cndmask_b32_e64 v115, v115, v159, s[88:89]
	v_cndmask_b32_e64 v119, v159, v119, s[88:89]
	global_store_dwordx4 v188, v[124:127], s[76:77]
	global_store_dwordx4 v189, v[120:123], s[76:77]
	global_store_dwordx4 v188, v[116:119], s[76:77] offset:128
	global_store_dwordx4 v189, v[112:115], s[76:77] offset:128
	s_add_u32 s76, s76, 0x10000
	s_addc_u32 s77, s77, 0
	v_pk_mul_f32 v[108:109], v[108:109], v[196:197] op_sel_hi:[1,0]
	v_pk_mul_f32 v[110:111], v[110:111], v[196:197] op_sel_hi:[1,0]
	v_pk_mul_f32 v[104:105], v[104:105], v[196:197] op_sel_hi:[1,0]
	v_pk_mul_f32 v[106:107], v[106:107], v[196:197] op_sel_hi:[1,0]
	v_pk_mul_f32 v[100:101], v[100:101], v[196:197] op_sel_hi:[1,0]
	v_pk_mul_f32 v[102:103], v[102:103], v[196:197] op_sel_hi:[1,0]
	v_pk_mul_f32 v[96:97], v[96:97], v[196:197] op_sel_hi:[1,0]
	v_pk_mul_f32 v[98:99], v[98:99], v[196:197] op_sel_hi:[1,0]
	v_pk_mul_f32 v[108:109], v[108:109], v[210:211]
	v_pk_mul_f32 v[110:111], v[110:111], v[212:213]
	v_pk_mul_f32 v[104:105], v[104:105], v[214:215]
	v_pk_mul_f32 v[106:107], v[106:107], v[216:217]
	v_pk_mul_f32 v[100:101], v[100:101], v[218:219]
	v_pk_mul_f32 v[102:103], v[102:103], v[220:221]
	v_pk_mul_f32 v[96:97], v[96:97], v[222:223]
	v_pk_mul_f32 v[98:99], v[98:99], v[224:225]
	v_cndmask_b32_e64 v136, v108, v104, s[88:89]
	v_cndmask_b32_e64 v137, v109, v105, s[88:89]
	v_cndmask_b32_e64 v138, v110, v106, s[88:89]
	v_cndmask_b32_e64 v139, v111, v107, s[88:89]
	v_mov_b32_dpp v156, v136 row_ror:8 row_mask:0xf bank_mask:0xf
	v_mov_b32_dpp v157, v137 row_ror:8 row_mask:0xf bank_mask:0xf
	v_mov_b32_dpp v158, v138 row_ror:8 row_mask:0xf bank_mask:0xf
	v_mov_b32_dpp v159, v139 row_ror:8 row_mask:0xf bank_mask:0xf
	v_cndmask_b32_e64 v104, v104, v156, s[88:89]
	v_cndmask_b32_e64 v108, v156, v108, s[88:89]
	v_cndmask_b32_e64 v105, v105, v157, s[88:89]
	v_cndmask_b32_e64 v109, v157, v109, s[88:89]
	v_cndmask_b32_e64 v106, v106, v158, s[88:89]
	v_cndmask_b32_e64 v110, v158, v110, s[88:89]
	v_cndmask_b32_e64 v107, v107, v159, s[88:89]
	v_cndmask_b32_e64 v111, v159, v111, s[88:89]
	v_cndmask_b32_e64 v136, v100, v96, s[88:89]
	v_cndmask_b32_e64 v137, v101, v97, s[88:89]
	v_cndmask_b32_e64 v138, v102, v98, s[88:89]
	v_cndmask_b32_e64 v139, v103, v99, s[88:89]
	v_mov_b32_dpp v156, v136 row_ror:8 row_mask:0xf bank_mask:0xf
	v_mov_b32_dpp v157, v137 row_ror:8 row_mask:0xf bank_mask:0xf
	v_mov_b32_dpp v158, v138 row_ror:8 row_mask:0xf bank_mask:0xf
	v_mov_b32_dpp v159, v139 row_ror:8 row_mask:0xf bank_mask:0xf
	v_cndmask_b32_e64 v96, v96, v156, s[88:89]
	v_cndmask_b32_e64 v100, v156, v100, s[88:89]
	v_cndmask_b32_e64 v97, v97, v157, s[88:89]
	v_cndmask_b32_e64 v101, v157, v101, s[88:89]
	v_cndmask_b32_e64 v98, v98, v158, s[88:89]
	v_cndmask_b32_e64 v102, v158, v102, s[88:89]
	v_cndmask_b32_e64 v99, v99, v159, s[88:89]
	v_cndmask_b32_e64 v103, v159, v103, s[88:89]
	global_store_dwordx4 v188, v[108:111], s[76:77]
	global_store_dwordx4 v189, v[104:107], s[76:77]
	global_store_dwordx4 v188, v[100:103], s[76:77] offset:128
	global_store_dwordx4 v189, v[96:99], s[76:77] offset:128
	s_add_u32 s76, s76, 0x10000
	s_addc_u32 s77, s77, 0
	v_pk_mul_f32 v[92:93], v[92:93], v[198:199] op_sel_hi:[1,0]
	v_pk_mul_f32 v[94:95], v[94:95], v[198:199] op_sel_hi:[1,0]
	v_pk_mul_f32 v[88:89], v[88:89], v[198:199] op_sel_hi:[1,0]
	v_pk_mul_f32 v[90:91], v[90:91], v[198:199] op_sel_hi:[1,0]
	v_pk_mul_f32 v[84:85], v[84:85], v[198:199] op_sel_hi:[1,0]
	v_pk_mul_f32 v[86:87], v[86:87], v[198:199] op_sel_hi:[1,0]
	v_pk_mul_f32 v[80:81], v[80:81], v[198:199] op_sel_hi:[1,0]
	v_pk_mul_f32 v[82:83], v[82:83], v[198:199] op_sel_hi:[1,0]
	v_pk_mul_f32 v[92:93], v[92:93], v[210:211]
	v_pk_mul_f32 v[94:95], v[94:95], v[212:213]
	v_pk_mul_f32 v[88:89], v[88:89], v[214:215]
	v_pk_mul_f32 v[90:91], v[90:91], v[216:217]
	v_pk_mul_f32 v[84:85], v[84:85], v[218:219]
	v_pk_mul_f32 v[86:87], v[86:87], v[220:221]
	v_pk_mul_f32 v[80:81], v[80:81], v[222:223]
	v_pk_mul_f32 v[82:83], v[82:83], v[224:225]
	v_cndmask_b32_e64 v136, v92, v88, s[88:89]
	v_cndmask_b32_e64 v137, v93, v89, s[88:89]
	v_cndmask_b32_e64 v138, v94, v90, s[88:89]
	v_cndmask_b32_e64 v139, v95, v91, s[88:89]
	v_mov_b32_dpp v156, v136 row_ror:8 row_mask:0xf bank_mask:0xf
	v_mov_b32_dpp v157, v137 row_ror:8 row_mask:0xf bank_mask:0xf
	v_mov_b32_dpp v158, v138 row_ror:8 row_mask:0xf bank_mask:0xf
	v_mov_b32_dpp v159, v139 row_ror:8 row_mask:0xf bank_mask:0xf
	v_cndmask_b32_e64 v88, v88, v156, s[88:89]
	v_cndmask_b32_e64 v92, v156, v92, s[88:89]
	v_cndmask_b32_e64 v89, v89, v157, s[88:89]
	v_cndmask_b32_e64 v93, v157, v93, s[88:89]
	v_cndmask_b32_e64 v90, v90, v158, s[88:89]
	v_cndmask_b32_e64 v94, v158, v94, s[88:89]
	v_cndmask_b32_e64 v91, v91, v159, s[88:89]
	v_cndmask_b32_e64 v95, v159, v95, s[88:89]
	v_cndmask_b32_e64 v136, v84, v80, s[88:89]
	v_cndmask_b32_e64 v137, v85, v81, s[88:89]
	v_cndmask_b32_e64 v138, v86, v82, s[88:89]
	v_cndmask_b32_e64 v139, v87, v83, s[88:89]
	v_mov_b32_dpp v156, v136 row_ror:8 row_mask:0xf bank_mask:0xf
	v_mov_b32_dpp v157, v137 row_ror:8 row_mask:0xf bank_mask:0xf
	v_mov_b32_dpp v158, v138 row_ror:8 row_mask:0xf bank_mask:0xf
	v_mov_b32_dpp v159, v139 row_ror:8 row_mask:0xf bank_mask:0xf
	v_cndmask_b32_e64 v80, v80, v156, s[88:89]
	v_cndmask_b32_e64 v84, v156, v84, s[88:89]
	v_cndmask_b32_e64 v81, v81, v157, s[88:89]
	v_cndmask_b32_e64 v85, v157, v85, s[88:89]
	v_cndmask_b32_e64 v82, v82, v158, s[88:89]
	v_cndmask_b32_e64 v86, v158, v86, s[88:89]
	v_cndmask_b32_e64 v83, v83, v159, s[88:89]
	v_cndmask_b32_e64 v87, v159, v87, s[88:89]
	global_store_dwordx4 v188, v[92:95], s[76:77]
	global_store_dwordx4 v189, v[88:91], s[76:77]
	global_store_dwordx4 v188, v[84:87], s[76:77] offset:128
	global_store_dwordx4 v189, v[80:83], s[76:77] offset:128
	s_add_u32 s76, s76, 0x10000
	s_addc_u32 s77, s77, 0
	v_pk_mul_f32 v[76:77], v[76:77], v[200:201] op_sel_hi:[1,0]
	v_pk_mul_f32 v[78:79], v[78:79], v[200:201] op_sel_hi:[1,0]
	v_pk_mul_f32 v[72:73], v[72:73], v[200:201] op_sel_hi:[1,0]
	v_pk_mul_f32 v[74:75], v[74:75], v[200:201] op_sel_hi:[1,0]
	v_pk_mul_f32 v[68:69], v[68:69], v[200:201] op_sel_hi:[1,0]
	v_pk_mul_f32 v[70:71], v[70:71], v[200:201] op_sel_hi:[1,0]
	v_pk_mul_f32 v[64:65], v[64:65], v[200:201] op_sel_hi:[1,0]
	v_pk_mul_f32 v[66:67], v[66:67], v[200:201] op_sel_hi:[1,0]
	v_pk_mul_f32 v[76:77], v[76:77], v[210:211]
	v_pk_mul_f32 v[78:79], v[78:79], v[212:213]
	v_pk_mul_f32 v[72:73], v[72:73], v[214:215]
	v_pk_mul_f32 v[74:75], v[74:75], v[216:217]
	v_pk_mul_f32 v[68:69], v[68:69], v[218:219]
	v_pk_mul_f32 v[70:71], v[70:71], v[220:221]
	v_pk_mul_f32 v[64:65], v[64:65], v[222:223]
	v_pk_mul_f32 v[66:67], v[66:67], v[224:225]
	v_cndmask_b32_e64 v136, v76, v72, s[88:89]
	v_cndmask_b32_e64 v137, v77, v73, s[88:89]
	v_cndmask_b32_e64 v138, v78, v74, s[88:89]
	v_cndmask_b32_e64 v139, v79, v75, s[88:89]
	v_mov_b32_dpp v156, v136 row_ror:8 row_mask:0xf bank_mask:0xf
	v_mov_b32_dpp v157, v137 row_ror:8 row_mask:0xf bank_mask:0xf
	v_mov_b32_dpp v158, v138 row_ror:8 row_mask:0xf bank_mask:0xf
	v_mov_b32_dpp v159, v139 row_ror:8 row_mask:0xf bank_mask:0xf
	v_cndmask_b32_e64 v72, v72, v156, s[88:89]
	v_cndmask_b32_e64 v76, v156, v76, s[88:89]
	v_cndmask_b32_e64 v73, v73, v157, s[88:89]
	v_cndmask_b32_e64 v77, v157, v77, s[88:89]
	v_cndmask_b32_e64 v74, v74, v158, s[88:89]
	v_cndmask_b32_e64 v78, v158, v78, s[88:89]
	v_cndmask_b32_e64 v75, v75, v159, s[88:89]
	v_cndmask_b32_e64 v79, v159, v79, s[88:89]
	v_cndmask_b32_e64 v136, v68, v64, s[88:89]
	v_cndmask_b32_e64 v137, v69, v65, s[88:89]
	v_cndmask_b32_e64 v138, v70, v66, s[88:89]
	v_cndmask_b32_e64 v139, v71, v67, s[88:89]
	v_mov_b32_dpp v156, v136 row_ror:8 row_mask:0xf bank_mask:0xf
	v_mov_b32_dpp v157, v137 row_ror:8 row_mask:0xf bank_mask:0xf
	v_mov_b32_dpp v158, v138 row_ror:8 row_mask:0xf bank_mask:0xf
	v_mov_b32_dpp v159, v139 row_ror:8 row_mask:0xf bank_mask:0xf
	v_cndmask_b32_e64 v64, v64, v156, s[88:89]
	v_cndmask_b32_e64 v68, v156, v68, s[88:89]
	v_cndmask_b32_e64 v65, v65, v157, s[88:89]
	v_cndmask_b32_e64 v69, v157, v69, s[88:89]
	v_cndmask_b32_e64 v66, v66, v158, s[88:89]
	v_cndmask_b32_e64 v70, v158, v70, s[88:89]
	v_cndmask_b32_e64 v67, v67, v159, s[88:89]
	v_cndmask_b32_e64 v71, v159, v71, s[88:89]
	global_store_dwordx4 v188, v[76:79], s[76:77]
	global_store_dwordx4 v189, v[72:75], s[76:77]
	global_store_dwordx4 v188, v[68:71], s[76:77] offset:128
	global_store_dwordx4 v189, v[64:67], s[76:77] offset:128
	s_add_u32 s76, s76, 0x50000
	s_addc_u32 s77, s77, 0
	v_pk_mul_f32 v[60:61], v[60:61], v[202:203] op_sel_hi:[1,0]
	v_pk_mul_f32 v[62:63], v[62:63], v[202:203] op_sel_hi:[1,0]
	v_pk_mul_f32 v[56:57], v[56:57], v[202:203] op_sel_hi:[1,0]
	v_pk_mul_f32 v[58:59], v[58:59], v[202:203] op_sel_hi:[1,0]
	v_pk_mul_f32 v[52:53], v[52:53], v[202:203] op_sel_hi:[1,0]
	v_pk_mul_f32 v[54:55], v[54:55], v[202:203] op_sel_hi:[1,0]
	v_pk_mul_f32 v[48:49], v[48:49], v[202:203] op_sel_hi:[1,0]
	v_pk_mul_f32 v[50:51], v[50:51], v[202:203] op_sel_hi:[1,0]
	v_pk_mul_f32 v[60:61], v[60:61], v[210:211]
	v_pk_mul_f32 v[62:63], v[62:63], v[212:213]
	v_pk_mul_f32 v[56:57], v[56:57], v[214:215]
	v_pk_mul_f32 v[58:59], v[58:59], v[216:217]
	v_pk_mul_f32 v[52:53], v[52:53], v[218:219]
	v_pk_mul_f32 v[54:55], v[54:55], v[220:221]
	v_pk_mul_f32 v[48:49], v[48:49], v[222:223]
	v_pk_mul_f32 v[50:51], v[50:51], v[224:225]
	v_cndmask_b32_e64 v136, v60, v56, s[88:89]
	v_cndmask_b32_e64 v137, v61, v57, s[88:89]
	v_cndmask_b32_e64 v138, v62, v58, s[88:89]
	v_cndmask_b32_e64 v139, v63, v59, s[88:89]
	v_mov_b32_dpp v156, v136 row_ror:8 row_mask:0xf bank_mask:0xf
	v_mov_b32_dpp v157, v137 row_ror:8 row_mask:0xf bank_mask:0xf
	v_mov_b32_dpp v158, v138 row_ror:8 row_mask:0xf bank_mask:0xf
	v_mov_b32_dpp v159, v139 row_ror:8 row_mask:0xf bank_mask:0xf
	v_cndmask_b32_e64 v56, v56, v156, s[88:89]
	v_cndmask_b32_e64 v60, v156, v60, s[88:89]
	v_cndmask_b32_e64 v57, v57, v157, s[88:89]
	v_cndmask_b32_e64 v61, v157, v61, s[88:89]
	v_cndmask_b32_e64 v58, v58, v158, s[88:89]
	v_cndmask_b32_e64 v62, v158, v62, s[88:89]
	v_cndmask_b32_e64 v59, v59, v159, s[88:89]
	v_cndmask_b32_e64 v63, v159, v63, s[88:89]
	v_cndmask_b32_e64 v136, v52, v48, s[88:89]
	v_cndmask_b32_e64 v137, v53, v49, s[88:89]
	v_cndmask_b32_e64 v138, v54, v50, s[88:89]
	v_cndmask_b32_e64 v139, v55, v51, s[88:89]
	v_mov_b32_dpp v156, v136 row_ror:8 row_mask:0xf bank_mask:0xf
	v_mov_b32_dpp v157, v137 row_ror:8 row_mask:0xf bank_mask:0xf
	v_mov_b32_dpp v158, v138 row_ror:8 row_mask:0xf bank_mask:0xf
	v_mov_b32_dpp v159, v139 row_ror:8 row_mask:0xf bank_mask:0xf
	v_cndmask_b32_e64 v48, v48, v156, s[88:89]
	v_cndmask_b32_e64 v52, v156, v52, s[88:89]
	v_cndmask_b32_e64 v49, v49, v157, s[88:89]
	v_cndmask_b32_e64 v53, v157, v53, s[88:89]
	v_cndmask_b32_e64 v50, v50, v158, s[88:89]
	v_cndmask_b32_e64 v54, v158, v54, s[88:89]
	v_cndmask_b32_e64 v51, v51, v159, s[88:89]
	v_cndmask_b32_e64 v55, v159, v55, s[88:89]
	global_store_dwordx4 v188, v[60:63], s[76:77]
	global_store_dwordx4 v189, v[56:59], s[76:77]
	global_store_dwordx4 v188, v[52:55], s[76:77] offset:128
	global_store_dwordx4 v189, v[48:51], s[76:77] offset:128
	s_add_u32 s76, s76, 0x10000
	s_addc_u32 s77, s77, 0
	v_pk_mul_f32 v[44:45], v[44:45], v[204:205] op_sel_hi:[1,0]
	v_pk_mul_f32 v[46:47], v[46:47], v[204:205] op_sel_hi:[1,0]
	v_pk_mul_f32 v[40:41], v[40:41], v[204:205] op_sel_hi:[1,0]
	v_pk_mul_f32 v[42:43], v[42:43], v[204:205] op_sel_hi:[1,0]
	v_pk_mul_f32 v[36:37], v[36:37], v[204:205] op_sel_hi:[1,0]
	v_pk_mul_f32 v[38:39], v[38:39], v[204:205] op_sel_hi:[1,0]
	v_pk_mul_f32 v[32:33], v[32:33], v[204:205] op_sel_hi:[1,0]
	v_pk_mul_f32 v[34:35], v[34:35], v[204:205] op_sel_hi:[1,0]
	v_pk_mul_f32 v[44:45], v[44:45], v[210:211]
	v_pk_mul_f32 v[46:47], v[46:47], v[212:213]
	v_pk_mul_f32 v[40:41], v[40:41], v[214:215]
	v_pk_mul_f32 v[42:43], v[42:43], v[216:217]
	v_pk_mul_f32 v[36:37], v[36:37], v[218:219]
	v_pk_mul_f32 v[38:39], v[38:39], v[220:221]
	v_pk_mul_f32 v[32:33], v[32:33], v[222:223]
	v_pk_mul_f32 v[34:35], v[34:35], v[224:225]
	v_cndmask_b32_e64 v136, v44, v40, s[88:89]
	v_cndmask_b32_e64 v137, v45, v41, s[88:89]
	v_cndmask_b32_e64 v138, v46, v42, s[88:89]
	v_cndmask_b32_e64 v139, v47, v43, s[88:89]
	v_mov_b32_dpp v156, v136 row_ror:8 row_mask:0xf bank_mask:0xf
	v_mov_b32_dpp v157, v137 row_ror:8 row_mask:0xf bank_mask:0xf
	v_mov_b32_dpp v158, v138 row_ror:8 row_mask:0xf bank_mask:0xf
	v_mov_b32_dpp v159, v139 row_ror:8 row_mask:0xf bank_mask:0xf
	v_cndmask_b32_e64 v40, v40, v156, s[88:89]
	v_cndmask_b32_e64 v44, v156, v44, s[88:89]
	v_cndmask_b32_e64 v41, v41, v157, s[88:89]
	v_cndmask_b32_e64 v45, v157, v45, s[88:89]
	v_cndmask_b32_e64 v42, v42, v158, s[88:89]
	v_cndmask_b32_e64 v46, v158, v46, s[88:89]
	v_cndmask_b32_e64 v43, v43, v159, s[88:89]
	v_cndmask_b32_e64 v47, v159, v47, s[88:89]
	v_cndmask_b32_e64 v136, v36, v32, s[88:89]
	v_cndmask_b32_e64 v137, v37, v33, s[88:89]
	v_cndmask_b32_e64 v138, v38, v34, s[88:89]
	v_cndmask_b32_e64 v139, v39, v35, s[88:89]
	v_mov_b32_dpp v156, v136 row_ror:8 row_mask:0xf bank_mask:0xf
	v_mov_b32_dpp v157, v137 row_ror:8 row_mask:0xf bank_mask:0xf
	v_mov_b32_dpp v158, v138 row_ror:8 row_mask:0xf bank_mask:0xf
	v_mov_b32_dpp v159, v139 row_ror:8 row_mask:0xf bank_mask:0xf
	v_cndmask_b32_e64 v32, v32, v156, s[88:89]
	v_cndmask_b32_e64 v36, v156, v36, s[88:89]
	v_cndmask_b32_e64 v33, v33, v157, s[88:89]
	v_cndmask_b32_e64 v37, v157, v37, s[88:89]
	v_cndmask_b32_e64 v34, v34, v158, s[88:89]
	v_cndmask_b32_e64 v38, v158, v38, s[88:89]
	v_cndmask_b32_e64 v35, v35, v159, s[88:89]
	v_cndmask_b32_e64 v39, v159, v39, s[88:89]
	global_store_dwordx4 v188, v[44:47], s[76:77]
	global_store_dwordx4 v189, v[40:43], s[76:77]
	global_store_dwordx4 v188, v[36:39], s[76:77] offset:128
	global_store_dwordx4 v189, v[32:35], s[76:77] offset:128
	s_add_u32 s76, s76, 0x10000
	s_addc_u32 s77, s77, 0
	v_pk_mul_f32 v[28:29], v[28:29], v[206:207] op_sel_hi:[1,0]
	v_pk_mul_f32 v[30:31], v[30:31], v[206:207] op_sel_hi:[1,0]
	v_pk_mul_f32 v[24:25], v[24:25], v[206:207] op_sel_hi:[1,0]
	v_pk_mul_f32 v[26:27], v[26:27], v[206:207] op_sel_hi:[1,0]
	v_pk_mul_f32 v[20:21], v[20:21], v[206:207] op_sel_hi:[1,0]
	v_pk_mul_f32 v[22:23], v[22:23], v[206:207] op_sel_hi:[1,0]
	v_pk_mul_f32 v[16:17], v[16:17], v[206:207] op_sel_hi:[1,0]
	v_pk_mul_f32 v[18:19], v[18:19], v[206:207] op_sel_hi:[1,0]
	v_pk_mul_f32 v[28:29], v[28:29], v[210:211]
	v_pk_mul_f32 v[30:31], v[30:31], v[212:213]
	v_pk_mul_f32 v[24:25], v[24:25], v[214:215]
	v_pk_mul_f32 v[26:27], v[26:27], v[216:217]
	v_pk_mul_f32 v[20:21], v[20:21], v[218:219]
	v_pk_mul_f32 v[22:23], v[22:23], v[220:221]
	v_pk_mul_f32 v[16:17], v[16:17], v[222:223]
	v_pk_mul_f32 v[18:19], v[18:19], v[224:225]
	v_cndmask_b32_e64 v136, v28, v24, s[88:89]
	v_cndmask_b32_e64 v137, v29, v25, s[88:89]
	v_cndmask_b32_e64 v138, v30, v26, s[88:89]
	v_cndmask_b32_e64 v139, v31, v27, s[88:89]
	v_mov_b32_dpp v156, v136 row_ror:8 row_mask:0xf bank_mask:0xf
	v_mov_b32_dpp v157, v137 row_ror:8 row_mask:0xf bank_mask:0xf
	v_mov_b32_dpp v158, v138 row_ror:8 row_mask:0xf bank_mask:0xf
	v_mov_b32_dpp v159, v139 row_ror:8 row_mask:0xf bank_mask:0xf
	v_cndmask_b32_e64 v24, v24, v156, s[88:89]
	v_cndmask_b32_e64 v28, v156, v28, s[88:89]
	v_cndmask_b32_e64 v25, v25, v157, s[88:89]
	v_cndmask_b32_e64 v29, v157, v29, s[88:89]
	v_cndmask_b32_e64 v26, v26, v158, s[88:89]
	v_cndmask_b32_e64 v30, v158, v30, s[88:89]
	v_cndmask_b32_e64 v27, v27, v159, s[88:89]
	v_cndmask_b32_e64 v31, v159, v31, s[88:89]
	v_cndmask_b32_e64 v136, v20, v16, s[88:89]
	v_cndmask_b32_e64 v137, v21, v17, s[88:89]
	v_cndmask_b32_e64 v138, v22, v18, s[88:89]
	v_cndmask_b32_e64 v139, v23, v19, s[88:89]
	v_mov_b32_dpp v156, v136 row_ror:8 row_mask:0xf bank_mask:0xf
	v_mov_b32_dpp v157, v137 row_ror:8 row_mask:0xf bank_mask:0xf
	v_mov_b32_dpp v158, v138 row_ror:8 row_mask:0xf bank_mask:0xf
	v_mov_b32_dpp v159, v139 row_ror:8 row_mask:0xf bank_mask:0xf
	v_cndmask_b32_e64 v16, v16, v156, s[88:89]
	v_cndmask_b32_e64 v20, v156, v20, s[88:89]
	v_cndmask_b32_e64 v17, v17, v157, s[88:89]
	v_cndmask_b32_e64 v21, v157, v21, s[88:89]
	v_cndmask_b32_e64 v18, v18, v158, s[88:89]
	v_cndmask_b32_e64 v22, v158, v22, s[88:89]
	v_cndmask_b32_e64 v19, v19, v159, s[88:89]
	v_cndmask_b32_e64 v23, v159, v23, s[88:89]
	global_store_dwordx4 v188, v[28:31], s[76:77]
	global_store_dwordx4 v189, v[24:27], s[76:77]
	global_store_dwordx4 v188, v[20:23], s[76:77] offset:128
	global_store_dwordx4 v189, v[16:19], s[76:77] offset:128
	s_add_u32 s76, s76, 0x10000
	s_addc_u32 s77, s77, 0
	v_pk_mul_f32 v[12:13], v[12:13], v[208:209] op_sel_hi:[1,0]
	v_pk_mul_f32 v[14:15], v[14:15], v[208:209] op_sel_hi:[1,0]
	v_pk_mul_f32 v[8:9], v[8:9], v[208:209] op_sel_hi:[1,0]
	v_pk_mul_f32 v[10:11], v[10:11], v[208:209] op_sel_hi:[1,0]
	v_pk_mul_f32 v[4:5], v[4:5], v[208:209] op_sel_hi:[1,0]
	v_pk_mul_f32 v[6:7], v[6:7], v[208:209] op_sel_hi:[1,0]
	v_pk_mul_f32 v[0:1], v[0:1], v[208:209] op_sel_hi:[1,0]
	v_pk_mul_f32 v[2:3], v[2:3], v[208:209] op_sel_hi:[1,0]
	v_pk_mul_f32 v[12:13], v[12:13], v[210:211]
	v_pk_mul_f32 v[14:15], v[14:15], v[212:213]
	v_pk_mul_f32 v[8:9], v[8:9], v[214:215]
	v_pk_mul_f32 v[10:11], v[10:11], v[216:217]
	v_pk_mul_f32 v[4:5], v[4:5], v[218:219]
	v_pk_mul_f32 v[6:7], v[6:7], v[220:221]
	v_pk_mul_f32 v[0:1], v[0:1], v[222:223]
	v_pk_mul_f32 v[2:3], v[2:3], v[224:225]
	v_cndmask_b32_e64 v136, v12, v8, s[88:89]
	v_cndmask_b32_e64 v137, v13, v9, s[88:89]
	v_cndmask_b32_e64 v138, v14, v10, s[88:89]
	v_cndmask_b32_e64 v139, v15, v11, s[88:89]
	v_mov_b32_dpp v156, v136 row_ror:8 row_mask:0xf bank_mask:0xf
	v_mov_b32_dpp v157, v137 row_ror:8 row_mask:0xf bank_mask:0xf
	v_mov_b32_dpp v158, v138 row_ror:8 row_mask:0xf bank_mask:0xf
	v_mov_b32_dpp v159, v139 row_ror:8 row_mask:0xf bank_mask:0xf
	v_cndmask_b32_e64 v8, v8, v156, s[88:89]
	v_cndmask_b32_e64 v12, v156, v12, s[88:89]
	v_cndmask_b32_e64 v9, v9, v157, s[88:89]
	v_cndmask_b32_e64 v13, v157, v13, s[88:89]
	v_cndmask_b32_e64 v10, v10, v158, s[88:89]
	v_cndmask_b32_e64 v14, v158, v14, s[88:89]
	v_cndmask_b32_e64 v11, v11, v159, s[88:89]
	v_cndmask_b32_e64 v15, v159, v15, s[88:89]
	v_cndmask_b32_e64 v136, v4, v0, s[88:89]
	v_cndmask_b32_e64 v137, v5, v1, s[88:89]
	v_cndmask_b32_e64 v138, v6, v2, s[88:89]
	v_cndmask_b32_e64 v139, v7, v3, s[88:89]
	v_mov_b32_dpp v156, v136 row_ror:8 row_mask:0xf bank_mask:0xf
	v_mov_b32_dpp v157, v137 row_ror:8 row_mask:0xf bank_mask:0xf
	v_mov_b32_dpp v158, v138 row_ror:8 row_mask:0xf bank_mask:0xf
	v_mov_b32_dpp v159, v139 row_ror:8 row_mask:0xf bank_mask:0xf
	v_cndmask_b32_e64 v0, v0, v156, s[88:89]
	v_cndmask_b32_e64 v4, v156, v4, s[88:89]
	v_cndmask_b32_e64 v1, v1, v157, s[88:89]
	v_cndmask_b32_e64 v5, v157, v5, s[88:89]
	v_cndmask_b32_e64 v2, v2, v158, s[88:89]
	v_cndmask_b32_e64 v6, v158, v6, s[88:89]
	v_cndmask_b32_e64 v3, v3, v159, s[88:89]
	v_cndmask_b32_e64 v7, v159, v7, s[88:89]
	global_store_dwordx4 v188, v[12:15], s[76:77]
	global_store_dwordx4 v189, v[8:11], s[76:77]
	global_store_dwordx4 v188, v[4:7], s[76:77] offset:128
	global_store_dwordx4 v189, v[0:3], s[76:77] offset:128
	s_cmpk_gt_u32 s17, 0xff
	s_cbranch_scc0 .Lf11_w0_b
	s_barrier
